# chain step split by function (waves 0,1 update state and publish bf16 state through LDS, waves 2,3 compute outputs) and only the 21 needed record pieces are DMAed per step by 3 waves; rest as previous
# baseline (speedup 1.0000x reference)
; __device__ __forceinline__ unsigned cvt_pk_bf16(float lo, float hi) { const f32x2_cv v = {lo, hi}; return __builtin_bit_cast(unsigned, __builtin_convertvector(v, bf16x2_cv)); }
; #define LAS __attribute__((address_space(3)))
; #define CH_RAWBAR() do { asm volatile("s_waitcnt lgkmcnt(0)" ::: "memory"); __builtin_amdgcn_s_barrier(); asm volatile("" ::: "memory"); } while (0)
; #define CH_WAIT(EX) do { if (wave < 3) CH_WAITN(8 + (EX)); else if (wave == 3) CH_WAITN(6 + (EX)); else CH_WAITN(6); } while (0)
; __device__ __forceinline__ void ch_issue(const unsigned char* Rl, LAS unsigned char* dst, int wave) {
;     __builtin_amdgcn_global_load_lds((const unsigned*)(Rl + wave * 1024), (LAS unsigned*)(dst + wave * 1024), 16, 0, 0);
;     __builtin_amdgcn_global_load_lds((const unsigned*)(Rl + (wave + 8) * 1024), (LAS unsigned*)(dst + (wave + 8) * 1024), 16, 0, 0);
;     __builtin_amdgcn_global_load_lds((const unsigned*)(Rl + (wave + 16) * 1024), (LAS unsigned*)(dst + (wave + 16) * 1024), 16, 0, 0);
;     if (wave < 3) __builtin_amdgcn_global_load_lds((const unsigned*)(Rl + (wave + 24) * 1024), (LAS unsigned*)(dst + (wave + 24) * 1024), 16, 0, 0);
; }
; __device__ __forceinline__ void hgrn_chain(const unsigned char* REC, const float* s0, float* sout, bf16_t* MIX,
;                                            int cidx0, int nchunks, int h, int vhalf, LAS unsigned char* lds, int wave, int lane) {
;     ...
;     bf16_t* mo = MIX + (size_t)(cidx0 * 32 + c16) * D + 1024 + h * 128 + v0 + 4 * g;
;     const unsigned char* Rl = REC + ((size_t)cidx0 * 8 + h) * REC_STRIDE + lane * 16;
;     const unsigned char* Rlast = Rl + (size_t)(nchunks - 1) * 8 * REC_STRIDE;
;     asm volatile("s_waitcnt vmcnt(0)" ::: "memory");
;     const unsigned char* Ri = Rl;
; #pragma unroll
;     for (int cc = 0; cc < CH_NS - 1; ++cc) { ch_issue(Ri, lds + cc * CH_SLOT, wave); Ri = Ri < Rlast ? Ri + 8 * REC_STRIDE : Rlast; }
;     CH_WAIT(0);
;     CH_RAWBAR();
;     ...
;             bf16x8 Sb[4];
; #pragma unroll
;             for (int kk = 0; kk < 4; ++kk) {
;                 u32x4 sb; sb.x = cvt_pk_bf16(S[2 * kk][0], S[2 * kk][1]); sb.y = cvt_pk_bf16(S[2 * kk][2], S[2 * kk][3]);
;                 sb.z = cvt_pk_bf16(S[2 * kk + 1][0], S[2 * kk + 1][1]); sb.w = cvt_pk_bf16(S[2 * kk + 1][2], S[2 * kk + 1][3]);
;                 Sb[kk] = __builtin_bit_cast(bf16x8, sb);
;             }
.LBB0_595:
	s_lshl_b32 s6, s79, 3
	s_and_b32 s8, s6, 0xffffff00
	s_ashr_i32 s10, s79, 2
	s_ashr_i32 s9, s8, 31
	s_and_b32 s11, s10, 7
	s_lshl_b64 s[6:7], s[8:9], 3
	s_or_b32 s6, s6, s11
	s_mulk_i32 s7, 0x6a00
	s_mul_hi_u32 s9, s6, 0x6a00
	s_add_i32 s9, s9, s7
	s_mulk_i32 s6, 0x6a00
	s_waitcnt vmcnt(0)
	v_mov_b32_e32 v10, v128
	s_add_u32 s6, s94, s6
	s_addc_u32 s7, s95, s9
	v_lshlrev_b32_e32 v120, 4, v10
	v_lshl_add_u64 v[0:1], s[6:7], 0, v[120:121]
	s_waitcnt vmcnt(0)
	s_and_b64 vcc, exec, s[88:89]
	s_cbranch_vccnz .Lch_pro_done
	s_cmp_eq_u32 s96, 0x1c00
	s_cbranch_scc1 .Lch_pro_done
	s_mov_b64 s[98:99], s[6:7]
	s_lshr_b32 s12, s96, 10
	s_sub_i32 s12, s12, 4
	s_mul_i32 s13, s12, 7
	s_and_b32 s100, s79, 3
	s_lshl_b32 s100, s100, 1
	s_add_i32 s100, s100, 16
	s_add_i32 s101, s100, 1
	s_add_i32 s6, s13, 0
	s_lshl_b32 s6, s6, 10
	v_add_u32_e32 v164, s6, v120
	s_add_i32 s6, s13, 1
	s_lshl_b32 s6, s6, 10
	v_add_u32_e32 v165, s6, v120
	s_add_i32 s6, s13, 2
	s_cmp_eq_u32 s12, 2
	s_cselect_b32 s6, s100, s6
	s_lshl_b32 s6, s6, 10
	v_add_u32_e32 v166, s6, v120
	s_add_i32 s6, s13, 3
	s_cmp_eq_u32 s12, 2
	s_cselect_b32 s6, s101, s6
	s_lshl_b32 s6, s6, 10
	v_add_u32_e32 v167, s6, v120
	s_add_i32 s6, s13, 4
	s_cmp_eq_u32 s12, 2
	s_cselect_b32 s6, 24, s6
	s_lshl_b32 s6, s6, 10
	v_add_u32_e32 v168, s6, v120
	s_add_i32 s6, s13, 5
	s_cmp_eq_u32 s12, 2
	s_cselect_b32 s6, 25, s6
	s_lshl_b32 s6, s6, 10
	v_add_u32_e32 v169, s6, v120
	s_add_i32 s6, s13, 6
	s_cmp_eq_u32 s12, 2
	s_cselect_b32 s6, 26, s6
	s_lshl_b32 s6, s6, 10
	v_add_u32_e32 v170, s6, v120
	s_mov_b64 s[12:13], s[98:99]
	s_mov_b32 s6, 0
	v_readfirstlane_b32 s7, v164
	s_add_i32 m0, s6, s7
	s_nop 0
	global_load_lds_dwordx4 v164, s[12:13]
	v_readfirstlane_b32 s7, v165
	s_add_i32 m0, s6, s7
	s_nop 0
	global_load_lds_dwordx4 v165, s[12:13]
	v_readfirstlane_b32 s7, v166
	s_add_i32 m0, s6, s7
	s_nop 0
	global_load_lds_dwordx4 v166, s[12:13]
	v_readfirstlane_b32 s7, v167
	s_add_i32 m0, s6, s7
	s_nop 0
	global_load_lds_dwordx4 v167, s[12:13]
	v_readfirstlane_b32 s7, v168
	s_add_i32 m0, s6, s7
	s_nop 0
	global_load_lds_dwordx4 v168, s[12:13]
	v_readfirstlane_b32 s7, v169
	s_add_i32 m0, s6, s7
	s_nop 0
	global_load_lds_dwordx4 v169, s[12:13]
	v_readfirstlane_b32 s7, v170
	s_add_i32 m0, s6, s7
	s_nop 0
	global_load_lds_dwordx4 v170, s[12:13]
	s_add_u32 s12, s98, 0x35000
	s_addc_u32 s13, s99, 0
	s_movk_i32 s6, 0x6c00
	v_readfirstlane_b32 s7, v164
	s_add_i32 m0, s6, s7
	s_nop 0
	global_load_lds_dwordx4 v164, s[12:13]
	v_readfirstlane_b32 s7, v165
	s_add_i32 m0, s6, s7
	s_nop 0
	global_load_lds_dwordx4 v165, s[12:13]
	v_readfirstlane_b32 s7, v166
	s_add_i32 m0, s6, s7
	s_nop 0
	global_load_lds_dwordx4 v166, s[12:13]
	v_readfirstlane_b32 s7, v167
	s_add_i32 m0, s6, s7
	s_nop 0
	global_load_lds_dwordx4 v167, s[12:13]
	v_readfirstlane_b32 s7, v168
	s_add_i32 m0, s6, s7
	s_nop 0
	global_load_lds_dwordx4 v168, s[12:13]
	v_readfirstlane_b32 s7, v169
	s_add_i32 m0, s6, s7
	s_nop 0
	global_load_lds_dwordx4 v169, s[12:13]
	v_readfirstlane_b32 s7, v170
	s_add_i32 m0, s6, s7
	s_nop 0
	global_load_lds_dwordx4 v170, s[12:13]
	s_add_u32 s12, s98, 0x6a000
	s_addc_u32 s13, s99, 0
	s_mov_b32 s6, 0xd800
	v_readfirstlane_b32 s7, v164
	s_add_i32 m0, s6, s7
	s_nop 0
	global_load_lds_dwordx4 v164, s[12:13]
	v_readfirstlane_b32 s7, v165
	s_add_i32 m0, s6, s7
	s_nop 0
	global_load_lds_dwordx4 v165, s[12:13]
	v_readfirstlane_b32 s7, v166
	s_add_i32 m0, s6, s7
	s_nop 0
	global_load_lds_dwordx4 v166, s[12:13]
	v_readfirstlane_b32 s7, v167
	s_add_i32 m0, s6, s7
	s_nop 0
	global_load_lds_dwordx4 v167, s[12:13]
	v_readfirstlane_b32 s7, v168
	s_add_i32 m0, s6, s7
	s_nop 0
	global_load_lds_dwordx4 v168, s[12:13]
	v_readfirstlane_b32 s7, v169
	s_add_i32 m0, s6, s7
	s_nop 0
	global_load_lds_dwordx4 v169, s[12:13]
	v_readfirstlane_b32 s7, v170
	s_add_i32 m0, s6, s7
	s_nop 0
	global_load_lds_dwordx4 v170, s[12:13]
	s_waitcnt vmcnt(14)
.Lch_pro_done:
	v_readlane_b32 s12, v236, 35
	s_cmp_lt_u32 s12, 2
	s_cbranch_scc0 .Lch_nozero
	s_and_b32 s12, s12, 1
	s_lshl_b32 s12, s12, 13
	s_add_i32 s12, s12, 0x1b000
	v_add_u32_e32 v168, s12, v120
	v_mov_b32_e32 v164, 0
	v_mov_b32_e32 v165, 0
	v_mov_b32_e32 v166, 0
	v_mov_b32_e32 v167, 0
	ds_write_b128 v168, v[164:167]
	ds_write_b128 v168, v[164:167] offset:1024
	ds_write_b128 v168, v[164:167] offset:2048
	ds_write_b128 v168, v[164:167] offset:3072

; __device__ __forceinline__ unsigned cvt_pk_bf16(float lo, float hi) { const f32x2_cv v = {lo, hi}; return __builtin_bit_cast(unsigned, __builtin_convertvector(v, bf16x2_cv)); }
; #define LAS __attribute__((address_space(3)))
; __device__ __forceinline__ void hgrn_chain(const unsigned char* REC, const float* s0, float* sout, bf16_t* MIX,
;                                            int cidx0, int nchunks, int h, int vhalf, LAS unsigned char* lds, int wave, int lane) {
;     ...
;         ch_issue(Ri, lds + islot * CH_SLOT, wave); Ri = Ri < Rlast ? Ri + 8 * REC_STRIDE : Rlast;
;         islot = islot == CH_NS - 1 ? 0 : islot + 1;
;         const LAS unsigned char* R = lds + slot * CH_SLOT;
;         slot = slot == CH_NS - 1 ? 0 : slot + 1;
;         if (comp) {
;             bf16x8 QDf[2][4], KEf[8], ITf, Af[2]; f32x4 DEC[8];
; #pragma unroll
;             for (int kb = 0; kb < 8; ++kb) { DEC[kb] = *(const LAS f32x4*)(R + R_DEC + (16 * kb + 4 * g) * 4); KEf[kb] = *(const LAS bf16x8*)(R + R_KE + ((16 * kb + c16) * 32 + 8 * g) * 2); }
;             ITf = *(const LAS bf16x8*)(R + R_IT + ((v0 + c16) * 32 + 8 * g) * 2);
; #pragma unroll
;             for (int tb = 0; tb < 2; ++tb) {
;                 Af[tb] = *(const LAS bf16x8*)(R + R_A + ((16 * tb + c16) * 32 + 8 * g) * 2);
; #pragma unroll
;                 for (int kk = 0; kk < 4; ++kk) QDf[tb][kk] = *(const LAS bf16x8*)(R + R_QD + ((tb * 4 + kk) * 64 + lane) * 16);
;             }
;             bf16x8 Sb[4];
; #pragma unroll
;             for (int kk = 0; kk < 4; ++kk) {
;                 u32x4 sb; sb.x = cvt_pk_bf16(S[2 * kk][0], S[2 * kk][1]); sb.y = cvt_pk_bf16(S[2 * kk][2], S[2 * kk][3]);
;                 sb.z = cvt_pk_bf16(S[2 * kk + 1][0], S[2 * kk + 1][1]); sb.w = cvt_pk_bf16(S[2 * kk + 1][2], S[2 * kk + 1][3]);
;                 Sb[kk] = __builtin_bit_cast(bf16x8, sb);
;             }
; #pragma unroll
;             for (int kb = 0; kb < 8; ++kb) S[kb] = __builtin_amdgcn_mfma_f32_16x16x32_bf16(KEf[kb], ITf, S[kb] * DEC[kb], 0, 0, 0);
.LBB0_605:
	s_and_b64 vcc, exec, s[88:89]
	s_cbranch_vccnz .Lch_comp_new
	s_mov_b64 s[8:9], -1
	s_cmp_eq_u32 s96, 0x1c00
	s_cbranch_scc1 .LBB0_604
	s_add_i32 s12, s11, 3
	s_min_u32 s12, s12, 0xff
	s_mul_i32 s12, s12, 0x35000
	s_add_u32 s12, s98, s12
	s_addc_u32 s13, s99, 0
	s_mul_i32 s6, s15, 0x6c00
	v_readfirstlane_b32 s7, v164
	s_add_i32 m0, s6, s7
	s_nop 0
	global_load_lds_dwordx4 v164, s[12:13]
	v_readfirstlane_b32 s7, v165
	s_add_i32 m0, s6, s7
	s_nop 0
	global_load_lds_dwordx4 v165, s[12:13]
	v_readfirstlane_b32 s7, v166
	s_add_i32 m0, s6, s7
	s_nop 0
	global_load_lds_dwordx4 v166, s[12:13]
	v_readfirstlane_b32 s7, v167
	s_add_i32 m0, s6, s7
	s_nop 0
	global_load_lds_dwordx4 v167, s[12:13]
	v_readfirstlane_b32 s7, v168
	s_add_i32 m0, s6, s7
	s_nop 0
	global_load_lds_dwordx4 v168, s[12:13]
	v_readfirstlane_b32 s7, v169
	s_add_i32 m0, s6, s7
	s_nop 0
	global_load_lds_dwordx4 v169, s[12:13]
	v_readfirstlane_b32 s7, v170
	s_add_i32 m0, s6, s7
	s_nop 0
	global_load_lds_dwordx4 v170, s[12:13]
	s_waitcnt vmcnt(14)
	s_branch .LBB0_604
.Lch_comp_new:
	v_readlane_b32 s12, v236, 35
	s_cmp_lt_u32 s12, 2
	s_cbranch_scc0 .Lch_out_entry
.Lch_upd_loop:
	s_mul_i32 s12, s16, 0x6c00
	v_add_u32_e32 v36, s12, v61
	v_add_u32_e32 v37, v36, v63
	v_add_u32_e32 v38, v36, v62
	ds_read_b128 v[32:35], v38 offset:16384
	ds_read_b128 v[164:167], v36 offset:26624
	ds_read_b128 v[196:199], v37 offset:8192
	ds_read_b128 v[168:171], v36 offset:26688
	ds_read_b128 v[200:203], v37 offset:9216
	ds_read_b128 v[172:175], v36 offset:26752
	ds_read_b128 v[204:207], v37 offset:10240
	ds_read_b128 v[176:179], v36 offset:26816
	ds_read_b128 v[208:211], v37 offset:11264
	ds_read_b128 v[180:183], v36 offset:26880
	ds_read_b128 v[212:215], v37 offset:12288
	ds_read_b128 v[184:187], v36 offset:26944
	ds_read_b128 v[216:219], v37 offset:13312
	ds_read_b128 v[188:191], v36 offset:27008
	ds_read_b128 v[220:223], v37 offset:14336
	s_mov_b64 s[8:9], 0
	v_readlane_b32 s13, v236, 35
	s_add_i32 s12, s11, 1
	s_and_b32 s12, s12, 1
	s_lshl_b32 s12, s12, 12
	s_and_b32 s13, s13, 1
	s_lshl_b32 s13, s13, 13
	s_add_i32 s12, s12, s13
	s_add_i32 s12, s12, 0x1b000
	v_add_u32_e32 v39, s12, v120
	s_waitcnt lgkmcnt(12)
	v_pk_mul_f32 v[28:29], v[28:29], v[164:165]
	v_pk_mul_f32 v[30:31], v[30:31], v[166:167]
	ds_read_b128 v[192:195], v36 offset:27072
	ds_read_b128 v[224:227], v37 offset:15360
	v_mfma_f32_16x16x32_bf16 v[28:31], v[196:199], v[32:35], v[28:31]
	s_waitcnt lgkmcnt(12)
	v_pk_mul_f32 v[24:25], v[24:25], v[168:169]
	v_pk_mul_f32 v[26:27], v[26:27], v[170:171]
	s_nop 1
	v_mfma_f32_16x16x32_bf16 v[24:27], v[200:203], v[32:35], v[24:27]
	s_waitcnt lgkmcnt(10)
	v_pk_mul_f32 v[20:21], v[20:21], v[172:173]
	v_pk_mul_f32 v[22:23], v[22:23], v[174:175]
	s_nop 1
	v_mfma_f32_16x16x32_bf16 v[20:23], v[204:207], v[32:35], v[20:23]
	s_waitcnt lgkmcnt(8)
	v_pk_mul_f32 v[16:17], v[16:17], v[176:177]
	v_pk_mul_f32 v[18:19], v[18:19], v[178:179]
	s_nop 1
	v_mfma_f32_16x16x32_bf16 v[16:19], v[208:211], v[32:35], v[16:19]
	s_waitcnt lgkmcnt(6)
	v_pk_mul_f32 v[12:13], v[12:13], v[180:181]
	v_pk_mul_f32 v[14:15], v[14:15], v[182:183]
	s_nop 1
	v_mfma_f32_16x16x32_bf16 v[12:15], v[212:215], v[32:35], v[12:15]
	s_waitcnt lgkmcnt(4)
	v_pk_mul_f32 v[8:9], v[8:9], v[184:185]
	v_pk_mul_f32 v[10:11], v[10:11], v[186:187]
	s_nop 1
	v_mfma_f32_16x16x32_bf16 v[8:11], v[216:219], v[32:35], v[8:11]
	s_waitcnt lgkmcnt(2)
	v_pk_mul_f32 v[4:5], v[4:5], v[188:189]
	v_pk_mul_f32 v[6:7], v[6:7], v[190:191]
	s_nop 1
	v_mfma_f32_16x16x32_bf16 v[4:7], v[220:223], v[32:35], v[4:7]
	s_waitcnt lgkmcnt(0)
	v_pk_mul_f32 v[0:1], v[0:1], v[192:193]
	v_pk_mul_f32 v[2:3], v[2:3], v[194:195]
	s_nop 1
	v_mfma_f32_16x16x32_bf16 v[0:3], v[224:227], v[32:35], v[0:3]
	s_nop 7
	v_cvt_pk_bf16_f32 v110, v28, v29
	v_cvt_pk_bf16_f32 v111, v30, v31
	v_cvt_pk_bf16_f32 v112, v24, v25
	v_cvt_pk_bf16_f32 v113, v26, v27
	v_cvt_pk_bf16_f32 v114, v20, v21
	v_cvt_pk_bf16_f32 v115, v22, v23
	v_cvt_pk_bf16_f32 v116, v16, v17
	v_cvt_pk_bf16_f32 v117, v18, v19
	v_cvt_pk_bf16_f32 v130, v12, v13
	v_cvt_pk_bf16_f32 v131, v14, v15
	v_cvt_pk_bf16_f32 v132, v8, v9
	v_cvt_pk_bf16_f32 v133, v10, v11
	v_cvt_pk_bf16_f32 v134, v4, v5
	v_cvt_pk_bf16_f32 v135, v6, v7
	v_cvt_pk_bf16_f32 v136, v0, v1
	v_cvt_pk_bf16_f32 v137, v2, v3
	ds_write_b128 v39, v[110:113]
	ds_write_b128 v39, v[114:117] offset:1024
	ds_write_b128 v39, v[130:133] offset:2048
	ds_write_b128 v39, v[134:137] offset:3072
	s_add_i32 s12, s16, 1
	s_cmp_lg_u32 s16, 3
	s_cselect_b32 s16, s12, 0
	s_add_i32 s11, s11, 1
	s_waitcnt lgkmcnt(0)
	s_barrier
	s_cmpk_eq_i32 s11, 0x100
	s_cbranch_scc0 .Lch_upd_loop
	s_branch .LBB0_639
; #define LAS __attribute__((address_space(3)))
; __device__ __forceinline__ void hgrn_chain(const unsigned char* REC, const float* s0, float* sout, bf16_t* MIX,
;                                            int cidx0, int nchunks, int h, int vhalf, LAS unsigned char* lds, int wave, int lane) {
;     ...
;             bf16x8 QDf[2][4], KEf[8], ITf, Af[2]; f32x4 DEC[8];
; #pragma unroll
;             for (int kb = 0; kb < 8; ++kb) { DEC[kb] = *(const LAS f32x4*)(R + R_DEC + (16 * kb + 4 * g) * 4); KEf[kb] = *(const LAS bf16x8*)(R + R_KE + ((16 * kb + c16) * 32 + 8 * g) * 2); }
;             ITf = *(const LAS bf16x8*)(R + R_IT + ((v0 + c16) * 32 + 8 * g) * 2);
; #pragma unroll
;             for (int tb = 0; tb < 2; ++tb) {
;                 Af[tb] = *(const LAS bf16x8*)(R + R_A + ((16 * tb + c16) * 32 + 8 * g) * 2);
; #pragma unroll
;                 for (int kk = 0; kk < 4; ++kk) QDf[tb][kk] = *(const LAS bf16x8*)(R + R_QD + ((tb * 4 + kk) * 64 + lane) * 16);
;             }
;             bf16x8 Sb[4];
; #pragma unroll
;             for (int kk = 0; kk < 4; ++kk) {
;                 u32x4 sb; sb.x = cvt_pk_bf16(S[2 * kk][0], S[2 * kk][1]); sb.y = cvt_pk_bf16(S[2 * kk][2], S[2 * kk][3]);
;                 sb.z = cvt_pk_bf16(S[2 * kk + 1][0], S[2 * kk + 1][1]); sb.w = cvt_pk_bf16(S[2 * kk + 1][2], S[2 * kk + 1][3]);
;                 Sb[kk] = __builtin_bit_cast(bf16x8, sb);
;             }
; #pragma unroll
;             for (int kb = 0; kb < 8; ++kb) S[kb] = __builtin_amdgcn_mfma_f32_16x16x32_bf16(KEf[kb], ITf, S[kb] * DEC[kb], 0, 0, 0);
;             f32x4 o0 = {0.f, 0.f, 0.f, 0.f}, o1 = o0;
;             o0 = __builtin_amdgcn_mfma_f32_16x16x32_bf16(ITf, Af[0], o0, 0, 0, 0);
;             o1 = __builtin_amdgcn_mfma_f32_16x16x32_bf16(ITf, Af[1], o1, 0, 0, 0);
; #pragma unroll
;             for (int kk = 0; kk < 4; ++kk) { o0 = __builtin_amdgcn_mfma_f32_16x16x32_bf16(Sb[kk], QDf[0][kk], o0, 0, 0, 0); o1 = __builtin_amdgcn_mfma_f32_16x16x32_bf16(Sb[kk], QDf[1][kk], o1, 0, 0, 0); }
;             u32x2 w; w.x = cvt_pk_bf16(o0[0], o0[1]); w.y = cvt_pk_bf16(o0[2], o0[3]);
;             *(u32x2*)(mo + (size_t)c * 32 * D) = w;
;             w.x = cvt_pk_bf16(o1[0], o1[1]); w.y = cvt_pk_bf16(o1[2], o1[3]);
;             *(u32x2*)(mo + (size_t)c * 32 * D + (size_t)16 * D) = w;
.Lch_out_entry:
	s_mov_b64 s[8:9], -1
.Lch_out_loop:
	s_mul_i32 s12, s16, 0x6c00
	v_add_u32_e32 v36, s12, v61
	v_add_u32_e32 v39, s12, v120
	v_add_u32_e32 v37, v36, v63
	v_add_u32_e32 v38, v36, v62
	v_readlane_b32 s13, v236, 35
	s_and_b32 s12, s11, 1
	s_lshl_b32 s12, s12, 12
	s_and_b32 s13, s13, 1
	s_lshl_b32 s13, s13, 13
	s_add_i32 s12, s12, s13
	s_add_i32 s12, s12, 0x1b000
	v_add_u32_e32 v40, s12, v120
	ds_read_b128 v[32:35], v38 offset:16384
	ds_read_b128 v[228:231], v37 offset:24576
	ds_read_b128 v[232:235], v37 offset:25600
	ds_read_b128 v[110:113], v40 offset:0
	ds_read_b128 v[78:81], v39 offset:0
	ds_read_b128 v[82:85], v39 offset:4096
	ds_read_b128 v[114:117], v40 offset:1024
	ds_read_b128 v[86:89], v39 offset:1024
	ds_read_b128 v[90:93], v39 offset:5120
	ds_read_b128 v[130:133], v40 offset:2048
	ds_read_b128 v[94:97], v39 offset:2048
	ds_read_b128 v[98:101], v39 offset:6144
	ds_read_b128 v[134:137], v40 offset:3072
	ds_read_b128 v[102:105], v39 offset:3072
	ds_read_b128 v[106:109], v39 offset:7168
	s_waitcnt lgkmcnt(12)
	v_mfma_f32_16x16x32_bf16 v[138:141], v[32:35], v[228:231], 0
	v_mfma_f32_16x16x32_bf16 v[146:149], v[32:35], v[232:235], 0
	s_waitcnt lgkmcnt(10)
	v_mfma_f32_16x16x32_bf16 v[138:141], v[110:113], v[78:81], v[138:141]
	s_waitcnt lgkmcnt(9)
	v_mfma_f32_16x16x32_bf16 v[146:149], v[110:113], v[82:85], v[146:149]
	s_waitcnt lgkmcnt(7)
	v_mfma_f32_16x16x32_bf16 v[138:141], v[114:117], v[86:89], v[138:141]
	s_waitcnt lgkmcnt(6)
	v_mfma_f32_16x16x32_bf16 v[146:149], v[114:117], v[90:93], v[146:149]
	s_waitcnt lgkmcnt(4)
	v_mfma_f32_16x16x32_bf16 v[138:141], v[130:133], v[94:97], v[138:141]
	s_waitcnt lgkmcnt(3)
	v_mfma_f32_16x16x32_bf16 v[146:149], v[130:133], v[98:101], v[146:149]
	s_waitcnt lgkmcnt(1)
	v_mfma_f32_16x16x32_bf16 v[138:141], v[134:137], v[102:105], v[138:141]
	s_waitcnt lgkmcnt(0)
	v_mfma_f32_16x16x32_bf16 v[146:149], v[134:137], v[106:109], v[146:149]
	s_mov_b32 s12, 0xffff0000
	s_nop 6
	v_cvt_pk_bf16_f32 v36, v138, v139
	v_cvt_pk_bf16_f32 v37, v140, v141
	v_add_co_u32_e32 v38, vcc, s12, v48
	v_cvt_pk_bf16_f32 v40, v146, v147
	s_nop 0
	v_addc_co_u32_e32 v39, vcc, -1, v49, vcc
	v_cvt_pk_bf16_f32 v41, v148, v149
	global_store_dwordx2 v[38:39], v[36:37], off
	global_store_dwordx2 v[48:49], v[40:41], off
	s_add_i32 s12, s16, 1
	s_cmp_lg_u32 s16, 3
	s_cselect_b32 s16, s12, 0
	s_add_i32 s11, s11, 1
	s_mov_b64 s[12:13], 0x20000
	v_lshl_add_u64 v[48:49], v[48:49], 0, s[12:13]
	s_waitcnt lgkmcnt(0)
	s_barrier
	s_cmpk_eq_i32 s11, 0x100
	s_cbranch_scc0 .Lch_out_loop
	s_branch .LBB0_639
